# steady attention loops: one static s_setprio 1 for waves 4-7 (reset at loop exit)
# speedup vs baseline: 1.0070x; 1.0070x over previous
.LBB0_971:
	s_and_b32 s16, s41, 0x3fffffc0
	s_cmp_lg_u32 0, -1
	v_lshlrev_b32_e32 v3, 1, v52
	s_cselect_b32 s3, 0, 0
	v_lshlrev_b32_e32 v4, 4, v52
	v_and_b32_e32 v3, 32, v3
	s_add_i32 s17, s3, 0x6000
	v_and_b32_e32 v4, 0xc0, v4
	v_add_u32_e32 v54, s17, v3
	v_lshl_or_b32 v55, v221, 8, v4
	v_add_u32_e32 v3, 0, v3
	v_add3_u32 v242, v3, v53, v55
	v_add3_u32 v238, v54, v53, v55
	v_max3_f32 v53, v34, v35, v18
	v_max3_f32 v54, v36, v37, v19
	s_lshl_b32 s16, s16, 2
	v_max3_f32 v53, v53, v20, v21
	v_max3_f32 v54, v54, v40, v41
	s_add_i32 s94, s16, 0
	v_max3_f32 v53, v53, v38, v39
	v_max3_f32 v54, v54, v24, v25
	s_add_i32 s17, s43, 0x100
	v_max3_f32 v53, v53, v22, v23
	v_max3_f32 v54, v54, v44, v45
	s_add_i32 s94, s94, 0x12000
	v_max3_f32 v53, v53, v42, v43
	v_max3_f32 v54, v54, v28, v29
	s_mov_b32 s6, 1
	v_max3_f32 v53, v53, v26, v27
	v_max3_f32 v54, v54, v48, v49
	s_mov_b32 s44, 0
	v_max3_f32 v53, v53, v46, v47
	v_max3_f32 v54, v54, v32, v33
	v_mov_b32_e32 v3, v2
	v_max3_f32 v53, v53, v30, v31
	v_mov_b32_e32 v4, v2
	v_max_f32_e32 v53, v53, v54
	v_mov_b32_e32 v5, v2
	v_mov_b32_e32 v54, v53
	s_nop 1
	v_permlane32_swap_b32_e32 v53, v54
	v_max_f32_e32 v53, v53, v54
	v_mov_b32_e32 v6, v2
	v_add_f32_e32 v240, v225, v53
	v_sub_f32_e32 v18, v18, v53
	v_sub_f32_e32 v19, v19, v53
	v_sub_f32_e32 v34, v34, v53
	v_sub_f32_e32 v35, v35, v53
	v_sub_f32_e32 v36, v36, v53
	s_nop 0
	v_xor_b32_e32 v66, 0x80000000, v240
	v_mov_b32_e32 v67, v66
	v_mov_b32_e32 v68, v66
	v_mov_b32_e32 v69, v66
	v_mov_b32_e32 v70, v66
	v_mov_b32_e32 v71, v66
	v_mov_b32_e32 v72, v66
	v_mov_b32_e32 v73, v66
	v_mov_b32_e32 v74, v66
	v_mov_b32_e32 v75, v66
	v_mov_b32_e32 v76, v66
	v_mov_b32_e32 v77, v66
	v_mov_b32_e32 v78, v66
	v_mov_b32_e32 v79, v66
	v_mov_b32_e32 v80, v66
	v_mov_b32_e32 v81, v66
	s_waitcnt vmcnt(0) lgkmcnt(0)
	s_barrier
	v_exp_f32_e32 v82, v18
	v_exp_f32_e32 v83, v19
	v_lshl_add_u64 v[18:19], v[226:227], 0, s[28:29]
	s_mov_b32 s16, m0
	s_mov_b32 m0, s83
	s_nop 0
	global_load_lds_dwordx4 v[18:19], off
	s_mov_b32 m0, s16
	s_add_i32 s16, s3, s2
	v_lshl_add_u64 v[18:19], v[50:51], 0, s[24:25]
	s_add_i32 s2, s16, 0xa000
	s_mov_b32 s3, m0
	s_mov_b32 m0, s2
	s_nop 0
	global_load_lds_dwordx4 v[18:19], off
	s_mov_b32 m0, s3
	s_mov_b64 s[2:3], 0x10080
	v_lshl_add_u64 v[18:19], v[50:51], 0, s[2:3]
	s_add_i32 s16, s16, 0xc000
	s_mov_b32 s2, m0
	s_mov_b32 m0, s16
	s_nop 0
	global_load_lds_dwordx4 v[18:19], off
	s_mov_b32 m0, s2
	ds_read_b128 v[206:209], v241 offset:8192
	ds_read_b128 v[202:205], v241 offset:8704
	ds_read_b128 v[198:201], v241 offset:10240
	ds_read_b128 v[194:197], v241 offset:10752
	ds_read_b128 v[190:193], v241 offset:12288
	ds_read_b128 v[186:189], v241 offset:12800
	ds_read_b128 v[182:185], v241 offset:14336
	ds_read_b128 v[178:181], v241 offset:14848
	v_sub_f32_e32 v20, v20, v53
	v_sub_f32_e32 v37, v37, v53
	v_sub_f32_e32 v21, v21, v53
	v_sub_f32_e32 v38, v38, v53
	v_sub_f32_e32 v22, v22, v53
	v_sub_f32_e32 v39, v39, v53
	v_sub_f32_e32 v23, v23, v53
	v_sub_f32_e32 v40, v40, v53
	v_sub_f32_e32 v24, v24, v53
	v_sub_f32_e32 v41, v41, v53
	v_sub_f32_e32 v25, v25, v53
	v_sub_f32_e32 v42, v42, v53
	v_sub_f32_e32 v26, v26, v53
	v_sub_f32_e32 v43, v43, v53
	v_sub_f32_e32 v27, v27, v53
	v_sub_f32_e32 v44, v44, v53
	v_sub_f32_e32 v28, v28, v53
	v_sub_f32_e32 v45, v45, v53
	v_sub_f32_e32 v29, v29, v53
	v_sub_f32_e32 v46, v46, v53
	v_sub_f32_e32 v30, v30, v53
	v_sub_f32_e32 v47, v47, v53
	v_sub_f32_e32 v31, v31, v53
	v_sub_f32_e32 v48, v48, v53
	v_sub_f32_e32 v32, v32, v53
	v_sub_f32_e32 v49, v49, v53
	v_sub_f32_e32 v33, v33, v53
	v_exp_f32_e32 v98, v34
	v_exp_f32_e32 v99, v35
	v_exp_f32_e32 v100, v36
	v_exp_f32_e32 v101, v37
	v_exp_f32_e32 v102, v38
	v_exp_f32_e32 v103, v39
	v_exp_f32_e32 v104, v40
	v_exp_f32_e32 v105, v41
	v_exp_f32_e32 v106, v42
	v_exp_f32_e32 v107, v43
	v_exp_f32_e32 v108, v44
	v_exp_f32_e32 v109, v45
	v_exp_f32_e32 v110, v46
	v_exp_f32_e32 v111, v47
	v_exp_f32_e32 v112, v48
	v_exp_f32_e32 v113, v49
	v_exp_f32_e32 v84, v20
	v_exp_f32_e32 v85, v21
	v_exp_f32_e32 v86, v22
	v_exp_f32_e32 v87, v23
	v_exp_f32_e32 v88, v24
	v_exp_f32_e32 v89, v25
	v_exp_f32_e32 v90, v26
	v_exp_f32_e32 v91, v27
	v_exp_f32_e32 v92, v28
	v_exp_f32_e32 v93, v29
	v_exp_f32_e32 v94, v30
	v_exp_f32_e32 v95, v31
	v_exp_f32_e32 v96, v32
	v_exp_f32_e32 v97, v33
	s_waitcnt vmcnt(3) lgkmcnt(0)
	s_barrier
	v_and_b32_e32 v18, 3, v52
	v_mov_b32_e32 v7, v2
	v_mov_b32_e32 v8, v2
	v_mov_b32_e32 v9, v2
	v_mov_b32_e32 v10, v2
	v_mov_b32_e32 v11, v2
	v_mov_b32_e32 v12, v2
	v_mov_b32_e32 v13, v2
	v_mov_b32_e32 v14, v2
	v_mov_b32_e32 v15, v2
	v_mov_b32_e32 v16, v2
	v_mov_b32_e32 v17, v2
	s_lshr_b32 s95, s17, 6
	s_andn2_b64 vcc, exec, s[0:1]
	v_cmp_gt_u32_e64 s[0:1], 32, v223
	v_lshlrev_b32_e32 v243, 4, v221
	v_lshl_add_u32 v237, v234, 2, s94
	v_lshlrev_b32_e32 v224, 4, v18
	s_cbranch_vccnz .LBB0_987
	s_lshl_b32 s2, s41, 8
	s_and_b32 s2, s2, 0xc000
	v_lshl_add_u64 v[18:19], s[4:5], 1, v[224:225]
	v_lshl_or_b32 v20, v220, 10, s2
	v_mov_b32_e32 v21, v225
	v_lshl_add_u64 v[18:19], v[18:19], 0, v[20:21]
	v_lshl_add_u64 v[214:215], s[22:23], 0, v[18:19]
	v_mov_b64_e32 v[64:65], v[16:17]
	v_mov_b64_e32 v[48:49], v[16:17]
	v_mov_b64_e32 v[32:33], v[16:17]
	s_add_i32 s42, s95, -5
	s_movk_i32 s46, 0x2000
	v_add_u32_e32 v228, 0x2000, v238
	s_movk_i32 s44, 0x4000
	s_mov_b32 s2, 0
	v_mov_b32_e32 v244, 0
	s_mov_b64 s[16:17], 0
	v_mov_b64_e32 v[62:63], v[14:15]
	v_mov_b64_e32 v[60:61], v[12:13]
	v_mov_b64_e32 v[58:59], v[10:11]
	v_mov_b64_e32 v[56:57], v[8:9]
	v_mov_b64_e32 v[54:55], v[6:7]
	v_mov_b64_e32 v[52:53], v[4:5]
	v_mov_b64_e32 v[50:51], v[2:3]
	v_mov_b64_e32 v[46:47], v[14:15]
	v_mov_b64_e32 v[44:45], v[12:13]
	v_mov_b64_e32 v[42:43], v[10:11]
	v_mov_b64_e32 v[40:41], v[8:9]
	v_mov_b64_e32 v[38:39], v[6:7]
	v_mov_b64_e32 v[36:37], v[4:5]
	v_mov_b64_e32 v[34:35], v[2:3]
	v_mov_b64_e32 v[30:31], v[14:15]
	v_mov_b64_e32 v[28:29], v[12:13]
	v_mov_b64_e32 v[26:27], v[10:11]
	v_mov_b64_e32 v[24:25], v[8:9]
	v_mov_b64_e32 v[22:23], v[6:7]
	v_mov_b64_e32 v[20:21], v[4:5]
	v_mov_b64_e32 v[18:19], v[2:3]
	v_readfirstlane_b32 s98, v226
	v_readfirstlane_b32 s99, v227
	v_readfirstlane_b32 s100, v214
	v_readfirstlane_b32 s101, v215
	s_mov_b32 s3, 0
	v_subrev_u32_e32 v218, s98, v226
	v_subrev_u32_e32 v219, s100, v214
	s_add_u32 s98, s98, s16
	s_addc_u32 s99, s99, s17
	s_add_u32 s98, s98, s30
	s_addc_u32 s99, s99, s31
	s_add_u32 s100, s100, s16
	s_addc_u32 s101, s101, s17
	s_add_u32 s100, s100, s34
	s_addc_u32 s101, s101, s35
	s_cmp_lt_u32 s83, 0x1000
	s_cbranch_scc1 .Lprio_a
	s_setprio 1
.Lprio_a:
.LBB0_973:
	s_lshl_b32 s40, s2, 1
	v_add_u32_e32 v216, s40, v242
	ds_read_b64_tr_b16 v[210:211], v216 offset:24576
	ds_read_b64_tr_b16 v[212:213], v216 offset:25088
	v_mfma_f32_32x32x16_bf16 v[130:145], v[206:209], v[174:177], v[66:81]
	v_add_f32_e32 v114, v98, v99
	v_add_f32_e32 v114, v100, v114
	v_add_f32_e32 v114, v101, v114
	v_add_f32_e32 v114, v102, v114
	v_add_f32_e32 v114, v103, v114
	v_cvt_pk_bf16_f32 v158, v98, v99
	v_cvt_pk_bf16_f32 v159, v100, v101
	ds_read_b64_tr_b16 v[206:207], v216 offset:28672
	ds_read_b64_tr_b16 v[208:209], v216 offset:29184
	v_add_f32_e32 v98, v104, v114
	v_mfma_f32_32x32x16_bf16 v[114:129], v[202:205], v[174:177], v[66:81]
	v_add_f32_e32 v98, v105, v98
	v_add_f32_e32 v98, v106, v98
	v_add_f32_e32 v146, v107, v98
	v_cvt_pk_bf16_f32 v160, v102, v103
	v_cvt_pk_bf16_f32 v161, v104, v105
	ds_read_b64_tr_b16 v[98:99], v216 offset:25600
	ds_read_b64_tr_b16 v[100:101], v216 offset:26112
	v_mfma_f32_32x32x16_bf16 v[130:145], v[198:201], v[170:173], v[130:145]
	v_add_f32_e32 v102, v108, v146
	v_add_f32_e32 v102, v109, v102
	v_add_f32_e32 v102, v110, v102
	v_add_f32_e32 v146, v111, v102
	v_cvt_pk_bf16_f32 v154, v106, v107
	v_cvt_pk_bf16_f32 v155, v108, v109
	ds_read_b64_tr_b16 v[102:103], v216 offset:29696
	ds_read_b64_tr_b16 v[104:105], v216 offset:30208
	v_mfma_f32_32x32x16_bf16 v[114:129], v[194:197], v[170:173], v[114:129]
	v_add_f32_e32 v106, v112, v146
	v_add_f32_e32 v106, v113, v106
	v_add_f32_e32 v106, v82, v106
	v_add_f32_e32 v146, v83, v106
	v_cvt_pk_bf16_f32 v156, v110, v111
	v_cvt_pk_bf16_f32 v157, v112, v113
	ds_read_b64_tr_b16 v[106:107], v216 offset:26624
	ds_read_b64_tr_b16 v[108:109], v216 offset:27136
	v_mfma_f32_32x32x16_bf16 v[130:145], v[190:193], v[166:169], v[130:145]
	v_add_f32_e32 v110, v84, v146
	v_add_f32_e32 v110, v85, v110
	v_add_f32_e32 v110, v86, v110
	v_add_f32_e32 v146, v87, v110
	v_cvt_pk_bf16_f32 v150, v82, v83
	v_cvt_pk_bf16_f32 v151, v84, v85
	ds_read_b64_tr_b16 v[110:111], v216 offset:30720
	ds_read_b64_tr_b16 v[112:113], v216 offset:31232
	v_mfma_f32_32x32x16_bf16 v[114:129], v[186:189], v[166:169], v[114:129]
	v_add_f32_e32 v82, v88, v146
	v_add_f32_e32 v82, v89, v82
	v_add_f32_e32 v82, v90, v82
	v_add_f32_e32 v82, v91, v82
	v_cvt_pk_bf16_f32 v152, v86, v87
	v_cvt_pk_bf16_f32 v153, v88, v89
	ds_read_b64_tr_b16 v[86:87], v216 offset:27648
	ds_read_b64_tr_b16 v[88:89], v216 offset:28160
	v_mfma_f32_32x32x16_bf16 v[130:145], v[182:185], v[162:165], v[130:145]
	v_add_f32_e32 v82, v92, v82
	v_add_f32_e32 v82, v93, v82
	v_add_f32_e32 v82, v94, v82
	v_add_f32_e32 v82, v95, v82
	v_cvt_pk_bf16_f32 v146, v90, v91
	v_cvt_pk_bf16_f32 v147, v92, v93
	ds_read_b64_tr_b16 v[90:91], v216 offset:31744
	ds_read_b64_tr_b16 v[92:93], v216 offset:32256
	v_mfma_f32_32x32x16_bf16 v[114:129], v[178:181], v[162:165], v[114:129]
	v_add_f32_e32 v82, v96, v82
	v_add_f32_e32 v82, v97, v82
	v_add_f32_e32 v230, v244, v82
	v_cvt_pk_bf16_f32 v148, v94, v95
	v_cvt_pk_bf16_f32 v149, v96, v97
	s_waitcnt lgkmcnt(8)
	v_mfma_f32_32x32x16_bf16 v[50:65], v[158:161], v[210:213], v[50:65]
	s_add_i32 m0, s46, s83
	s_lshl_b32 s2, s44, 1
	global_load_lds_dwordx4 v218, s[98:99]
	s_add_i32 m0, s2, s84
	s_add_u32 s98, s98, 0x10000
	s_addc_u32 s99, s99, 0
	global_load_lds_dwordx4 v219, s[100:101]
	s_addk_i32 m0, 0x1f80
	v_mfma_f32_32x32x16_bf16 v[34:49], v[158:161], v[206:209], v[34:49]
	global_load_lds_dwordx4 v219, s[100:101] offset:128
	s_add_u32 s100, s100, 0x10000
	s_addc_u32 s101, s101, 0
	v_mfma_f32_32x32x16_bf16 v[50:65], v[154:157], v[98:101], v[50:65]
	v_max_f32_e32 v82, v130, v131
	v_max3_f32 v83, v132, v133, v115
	v_max3_f32 v82, v82, v114, v116
	v_max3_f32 v82, v82, v117, v134
	v_max3_f32 v83, v83, v136, v137
	v_max3_f32 v82, v82, v135, v118
	v_max3_f32 v83, v83, v120, v121
	v_max3_f32 v82, v82, v119, v138
	v_mfma_f32_32x32x16_bf16 v[34:49], v[154:157], v[102:105], v[34:49]
	v_max3_f32 v83, v83, v140, v141
	v_max3_f32 v82, v82, v139, v122
	v_max3_f32 v83, v83, v124, v125
	v_max3_f32 v82, v82, v123, v142
	v_max3_f32 v83, v83, v144, v145
	v_max3_f32 v82, v82, v143, v126
	v_max3_f32 v83, v83, v128, v129
	v_max3_f32 v82, v82, v127, v83
	v_mov_b32_e32 v83, v82
	v_add_u32_e32 v94, s44, v241
	v_add_u32_e32 v102, s40, v228
	v_permlane32_swap_b32_e32 v82, v83
	v_max_f32_e32 v82, v82, v83
	v_cmp_lt_f32_e32 vcc, s87, v82
	s_cbranch_vccnz .LBB0_981

.LBB0_988:
	s_setprio 0
	s_add_i32 s0, s6, 1
	s_cmp_lt_i32 s0, s95
	s_cbranch_scc1 .LBB0_996
	s_lshl_b32 s42, s44, 1
	v_lshlrev_b32_e32 v114, 2, v221
	s_cbranch_execz .LBB0_997
	v_mov_b32_e32 v236, v114

.LBB0_1077:
	s_and_b32 s1, s41, 0x3fffffc0
	s_cmp_lg_u32 0, -1
	v_lshlrev_b32_e32 v3, 1, v52
	s_cselect_b32 s0, 0, 0
	v_lshlrev_b32_e32 v4, 4, v52
	v_and_b32_e32 v3, 32, v3
	s_add_i32 s3, s0, 0x6000
	v_and_b32_e32 v4, 0xc0, v4
	v_add_u32_e32 v54, s3, v3
	v_lshl_or_b32 v55, v220, 8, v4
	v_add_u32_e32 v3, 0, v3
	v_add3_u32 v242, v3, v53, v55
	v_add3_u32 v237, v54, v53, v55
	v_max3_f32 v53, v34, v35, v18
	v_max3_f32 v54, v36, v37, v19
	s_lshl_b32 s1, s1, 2
	v_max3_f32 v53, v53, v20, v21
	v_max3_f32 v54, v54, v40, v41
	s_add_i32 s39, s1, 0
	v_max3_f32 v53, v53, v38, v39
	v_max3_f32 v54, v54, v24, v25
	s_add_i32 s2, s0, s2
	v_max3_f32 v53, v53, v22, v23
	v_max3_f32 v54, v54, v44, v45
	s_add_i32 s0, s2, 0xa000
	v_max3_f32 v53, v53, v42, v43
	v_max3_f32 v54, v54, v28, v29
	s_add_i32 s2, s2, 0xc000
	v_max3_f32 v53, v53, v26, v27
	v_max3_f32 v54, v54, v48, v49
	s_add_i32 s39, s39, 0x12000
	v_max3_f32 v53, v53, v46, v47
	v_max3_f32 v54, v54, v32, v33
	s_mov_b32 s8, 1
	v_max3_f32 v53, v53, v30, v31
	s_mov_b32 s43, 0
	v_max_f32_e32 v53, v53, v54
	v_mov_b32_e32 v3, v2
	v_mov_b32_e32 v54, v53
	s_nop 1
	v_permlane32_swap_b32_e32 v53, v54
	v_max_f32_e32 v53, v53, v54
	v_mov_b32_e32 v4, v2
	v_add_f32_e32 v240, v225, v53
	v_sub_f32_e32 v18, v18, v53
	v_sub_f32_e32 v19, v19, v53
	v_sub_f32_e32 v34, v34, v53
	v_sub_f32_e32 v35, v35, v53
	v_sub_f32_e32 v36, v36, v53
	s_nop 0
	v_xor_b32_e32 v66, 0x80000000, v240
	v_mov_b32_e32 v67, v66
	v_mov_b32_e32 v68, v66
	v_mov_b32_e32 v69, v66
	v_mov_b32_e32 v70, v66
	v_mov_b32_e32 v71, v66
	v_mov_b32_e32 v72, v66
	v_mov_b32_e32 v73, v66
	v_mov_b32_e32 v74, v66
	v_mov_b32_e32 v75, v66
	v_mov_b32_e32 v76, v66
	v_mov_b32_e32 v77, v66
	v_mov_b32_e32 v78, v66
	v_mov_b32_e32 v79, v66
	v_mov_b32_e32 v80, v66
	v_mov_b32_e32 v81, v66
	s_waitcnt vmcnt(0) lgkmcnt(0)
	s_barrier
	v_exp_f32_e32 v82, v18
	v_exp_f32_e32 v83, v19
	v_lshl_add_u64 v[18:19], v[226:227], 0, s[20:21]
	s_mov_b32 s1, m0
	s_mov_b32 m0, s44
	s_nop 0
	global_load_lds_dwordx4 v[18:19], off
	s_mov_b32 m0, s1
	v_lshl_add_u64 v[18:19], v[50:51], 0, s[10:11]
	s_mov_b32 s1, m0
	s_mov_b32 m0, s0
	s_nop 0
	global_load_lds_dwordx4 v[18:19], off
	s_mov_b32 m0, s1
	s_mov_b64 s[0:1], 0x10080
	v_lshl_add_u64 v[18:19], v[50:51], 0, s[0:1]
	s_mov_b32 s0, m0
	s_mov_b32 m0, s2
	s_nop 0
	global_load_lds_dwordx4 v[18:19], off
	s_mov_b32 m0, s0
	ds_read_b128 v[206:209], v241 offset:8192
	ds_read_b128 v[198:201], v241 offset:8704
	ds_read_b128 v[202:205], v241 offset:10240
	ds_read_b128 v[194:197], v241 offset:10752
	ds_read_b128 v[190:193], v241 offset:12288
	ds_read_b128 v[186:189], v241 offset:12800
	ds_read_b128 v[182:185], v241 offset:14336
	ds_read_b128 v[178:181], v241 offset:14848
	v_sub_f32_e32 v20, v20, v53
	v_sub_f32_e32 v37, v37, v53
	v_sub_f32_e32 v21, v21, v53
	v_sub_f32_e32 v38, v38, v53
	v_sub_f32_e32 v22, v22, v53
	v_sub_f32_e32 v39, v39, v53
	v_sub_f32_e32 v23, v23, v53
	v_sub_f32_e32 v40, v40, v53
	v_sub_f32_e32 v24, v24, v53
	v_sub_f32_e32 v41, v41, v53
	v_sub_f32_e32 v25, v25, v53
	v_sub_f32_e32 v42, v42, v53
	v_sub_f32_e32 v26, v26, v53
	v_sub_f32_e32 v43, v43, v53
	v_sub_f32_e32 v27, v27, v53
	v_sub_f32_e32 v44, v44, v53
	v_sub_f32_e32 v28, v28, v53
	v_sub_f32_e32 v45, v45, v53
	v_sub_f32_e32 v29, v29, v53
	v_sub_f32_e32 v46, v46, v53
	v_sub_f32_e32 v30, v30, v53
	v_sub_f32_e32 v47, v47, v53
	v_sub_f32_e32 v31, v31, v53
	v_sub_f32_e32 v48, v48, v53
	v_sub_f32_e32 v32, v32, v53
	v_sub_f32_e32 v49, v49, v53
	v_sub_f32_e32 v33, v33, v53
	v_exp_f32_e32 v98, v34
	v_exp_f32_e32 v99, v35
	v_exp_f32_e32 v100, v36
	v_exp_f32_e32 v101, v37
	v_exp_f32_e32 v102, v38
	v_exp_f32_e32 v103, v39
	v_exp_f32_e32 v104, v40
	v_exp_f32_e32 v105, v41
	v_exp_f32_e32 v106, v42
	v_exp_f32_e32 v107, v43
	v_exp_f32_e32 v108, v44
	v_exp_f32_e32 v109, v45
	v_exp_f32_e32 v110, v46
	v_exp_f32_e32 v111, v47
	v_exp_f32_e32 v112, v48
	v_exp_f32_e32 v113, v49
	v_exp_f32_e32 v84, v20
	v_exp_f32_e32 v85, v21
	v_exp_f32_e32 v86, v22
	v_exp_f32_e32 v87, v23
	v_exp_f32_e32 v88, v24
	v_exp_f32_e32 v89, v25
	v_exp_f32_e32 v90, v26
	v_exp_f32_e32 v91, v27
	v_exp_f32_e32 v92, v28
	v_exp_f32_e32 v93, v29
	v_exp_f32_e32 v94, v30
	v_exp_f32_e32 v95, v31
	v_exp_f32_e32 v96, v32
	v_exp_f32_e32 v97, v33
	s_waitcnt vmcnt(3) lgkmcnt(0)
	s_barrier
	v_and_b32_e32 v18, 3, v52
	v_mov_b32_e32 v5, v2
	v_mov_b32_e32 v6, v2
	v_mov_b32_e32 v7, v2
	v_mov_b32_e32 v8, v2
	v_mov_b32_e32 v9, v2
	v_mov_b32_e32 v10, v2
	v_mov_b32_e32 v11, v2
	v_mov_b32_e32 v12, v2
	v_mov_b32_e32 v13, v2
	v_mov_b32_e32 v14, v2
	v_mov_b32_e32 v15, v2
	v_mov_b32_e32 v16, v2
	v_mov_b32_e32 v17, v2
	s_cmp_lt_i32 s46, 7
	v_cmp_gt_u32_e64 s[0:1], 32, v223
	v_lshlrev_b32_e32 v243, 4, v220
	v_lshl_add_u32 v238, v234, 2, s39
	v_lshlrev_b32_e32 v224, 4, v18
	s_cbranch_scc1 .LBB0_1093
	s_add_i32 s42, s46, -5
	s_lshl_b64 s[2:3], s[30:31], 1
	s_add_u32 s2, s2, s16
	s_addc_u32 s3, s3, s17
	s_add_u32 s2, s2, s4
	s_addc_u32 s3, s3, s5
	v_lshl_add_u64 v[18:19], s[2:3], 0, v[224:225]
	s_lshl_b32 s2, s41, 8
	s_and_b32 s2, s2, 0xc000
	v_lshl_or_b32 v20, v221, 10, s2
	v_mov_b32_e32 v21, v225
	v_readlane_b32 s52, v254, 6
	v_lshl_add_u64 v[18:19], v[18:19], 0, v[20:21]
	v_readlane_b32 s58, v254, 12
	v_readlane_b32 s59, v254, 13
	v_mov_b64_e32 v[64:65], v[16:17]
	v_mov_b64_e32 v[48:49], v[16:17]
	v_lshl_add_u64 v[214:215], s[58:59], 0, v[18:19]
	v_mov_b64_e32 v[32:33], v[16:17]
	s_movk_i32 s48, 0x2000
	v_add_u32_e32 v228, 0x2000, v237
	s_movk_i32 s43, 0x4000
	s_mov_b32 s2, 0
	v_mov_b32_e32 v244, 0
	s_mov_b64 s[34:35], 0
	v_mov_b64_e32 v[62:63], v[14:15]
	v_mov_b64_e32 v[60:61], v[12:13]
	v_mov_b64_e32 v[58:59], v[10:11]
	v_mov_b64_e32 v[56:57], v[8:9]
	v_mov_b64_e32 v[54:55], v[6:7]
	v_mov_b64_e32 v[52:53], v[4:5]
	v_mov_b64_e32 v[50:51], v[2:3]
	v_mov_b64_e32 v[46:47], v[14:15]
	v_mov_b64_e32 v[44:45], v[12:13]
	v_mov_b64_e32 v[42:43], v[10:11]
	v_mov_b64_e32 v[40:41], v[8:9]
	v_mov_b64_e32 v[38:39], v[6:7]
	v_mov_b64_e32 v[36:37], v[4:5]
	v_mov_b64_e32 v[34:35], v[2:3]
	v_mov_b64_e32 v[30:31], v[14:15]
	v_mov_b64_e32 v[28:29], v[12:13]
	v_mov_b64_e32 v[26:27], v[10:11]
	v_mov_b64_e32 v[24:25], v[8:9]
	v_mov_b64_e32 v[22:23], v[6:7]
	v_mov_b64_e32 v[20:21], v[4:5]
	v_mov_b64_e32 v[18:19], v[2:3]
	v_readlane_b32 s53, v254, 7
	v_readlane_b32 s54, v254, 8
	v_readlane_b32 s55, v254, 9
	v_readlane_b32 s56, v254, 10
	v_readlane_b32 s57, v254, 11
	v_readfirstlane_b32 s98, v226
	v_readfirstlane_b32 s99, v227
	v_readfirstlane_b32 s100, v214
	v_readfirstlane_b32 s101, v215
	s_mov_b32 s3, 0
	v_subrev_u32_e32 v218, s98, v226
	v_subrev_u32_e32 v219, s100, v214
	s_add_u32 s98, s98, s34
	s_addc_u32 s99, s99, s35
	s_add_u32 s98, s98, s22
	s_addc_u32 s99, s99, s23
	s_add_u32 s100, s100, s34
	s_addc_u32 s101, s101, s35
	s_add_u32 s100, s100, s24
	s_addc_u32 s101, s101, s25
	s_cmp_lt_u32 s44, 0x1000
	s_cbranch_scc1 .Lprio_b
	s_setprio 1
.Lprio_b:
.LBB0_1079:
	s_lshl_b32 s40, s2, 1
	v_add_u32_e32 v216, s40, v242
	ds_read_b64_tr_b16 v[210:211], v216 offset:24576
	ds_read_b64_tr_b16 v[212:213], v216 offset:25088
	v_mfma_f32_32x32x16_bf16 v[130:145], v[206:209], v[174:177], v[66:81]
	v_add_f32_e32 v114, v98, v99
	v_add_f32_e32 v114, v100, v114
	v_add_f32_e32 v114, v101, v114
	v_add_f32_e32 v114, v102, v114
	v_add_f32_e32 v114, v103, v114
	v_cvt_pk_bf16_f32 v166, v98, v99
	v_cvt_pk_bf16_f32 v167, v100, v101
	ds_read_b64_tr_b16 v[206:207], v216 offset:28672
	ds_read_b64_tr_b16 v[208:209], v216 offset:29184
	v_add_f32_e32 v98, v104, v114
	v_mfma_f32_32x32x16_bf16 v[114:129], v[198:201], v[174:177], v[66:81]
	v_add_f32_e32 v98, v105, v98
	v_add_f32_e32 v98, v106, v98
	v_add_f32_e32 v154, v107, v98
	v_cvt_pk_bf16_f32 v168, v102, v103
	v_cvt_pk_bf16_f32 v169, v104, v105
	ds_read_b64_tr_b16 v[98:99], v216 offset:25600
	ds_read_b64_tr_b16 v[100:101], v216 offset:26112
	v_mfma_f32_32x32x16_bf16 v[130:145], v[202:205], v[170:173], v[130:145]
	v_add_f32_e32 v102, v108, v154
	v_add_f32_e32 v102, v109, v102
	v_add_f32_e32 v102, v110, v102
	v_add_f32_e32 v154, v111, v102
	v_cvt_pk_bf16_f32 v162, v106, v107
	v_cvt_pk_bf16_f32 v163, v108, v109
	ds_read_b64_tr_b16 v[102:103], v216 offset:29696
	ds_read_b64_tr_b16 v[104:105], v216 offset:30208
	v_mfma_f32_32x32x16_bf16 v[114:129], v[194:197], v[170:173], v[114:129]
	v_add_f32_e32 v106, v112, v154
	v_add_f32_e32 v106, v113, v106
	v_add_f32_e32 v106, v82, v106
	v_add_f32_e32 v154, v83, v106
	v_cvt_pk_bf16_f32 v164, v110, v111
	v_cvt_pk_bf16_f32 v165, v112, v113
	ds_read_b64_tr_b16 v[106:107], v216 offset:26624
	ds_read_b64_tr_b16 v[108:109], v216 offset:27136
	v_mfma_f32_32x32x16_bf16 v[130:145], v[190:193], v[150:153], v[130:145]
	v_add_f32_e32 v110, v84, v154
	v_add_f32_e32 v110, v85, v110
	v_add_f32_e32 v110, v86, v110
	v_add_f32_e32 v154, v87, v110
	v_cvt_pk_bf16_f32 v158, v82, v83
	v_cvt_pk_bf16_f32 v159, v84, v85
	ds_read_b64_tr_b16 v[110:111], v216 offset:30720
	ds_read_b64_tr_b16 v[112:113], v216 offset:31232
	v_mfma_f32_32x32x16_bf16 v[114:129], v[186:189], v[150:153], v[114:129]
	v_add_f32_e32 v82, v88, v154
	v_add_f32_e32 v82, v89, v82
	v_add_f32_e32 v82, v90, v82
	v_add_f32_e32 v82, v91, v82
	v_cvt_pk_bf16_f32 v160, v86, v87
	v_cvt_pk_bf16_f32 v161, v88, v89
	ds_read_b64_tr_b16 v[86:87], v216 offset:27648
	ds_read_b64_tr_b16 v[88:89], v216 offset:28160
	v_mfma_f32_32x32x16_bf16 v[130:145], v[182:185], v[146:149], v[130:145]
	v_add_f32_e32 v82, v92, v82
	v_add_f32_e32 v82, v93, v82
	v_add_f32_e32 v82, v94, v82
	v_add_f32_e32 v82, v95, v82
	v_cvt_pk_bf16_f32 v154, v90, v91
	v_cvt_pk_bf16_f32 v155, v92, v93
	ds_read_b64_tr_b16 v[90:91], v216 offset:31744
	ds_read_b64_tr_b16 v[92:93], v216 offset:32256
	v_mfma_f32_32x32x16_bf16 v[114:129], v[178:181], v[146:149], v[114:129]
	v_add_f32_e32 v82, v96, v82
	v_add_f32_e32 v82, v97, v82
	v_add_f32_e32 v230, v244, v82
	v_cvt_pk_bf16_f32 v156, v94, v95
	v_cvt_pk_bf16_f32 v157, v96, v97
	s_waitcnt lgkmcnt(8)
	v_mfma_f32_32x32x16_bf16 v[50:65], v[166:169], v[210:213], v[50:65]
	s_add_i32 m0, s48, s44
	s_lshl_b32 s2, s43, 1
	global_load_lds_dwordx4 v218, s[98:99]
	s_add_i32 m0, s2, s45
	s_add_u32 s98, s98, 0x10000
	s_addc_u32 s99, s99, 0
	global_load_lds_dwordx4 v219, s[100:101]
	s_addk_i32 m0, 0x1f80
	v_mfma_f32_32x32x16_bf16 v[34:49], v[166:169], v[206:209], v[34:49]
	global_load_lds_dwordx4 v219, s[100:101] offset:128
	s_add_u32 s100, s100, 0x10000
	s_addc_u32 s101, s101, 0
	v_mfma_f32_32x32x16_bf16 v[50:65], v[162:165], v[98:101], v[50:65]
	v_max_f32_e32 v82, v130, v131
	v_max3_f32 v83, v132, v133, v115
	v_max3_f32 v82, v82, v114, v116
	v_max3_f32 v82, v82, v117, v134
	v_max3_f32 v83, v83, v136, v137
	v_max3_f32 v82, v82, v135, v118
	v_max3_f32 v83, v83, v120, v121
	v_max3_f32 v82, v82, v119, v138
	v_mfma_f32_32x32x16_bf16 v[34:49], v[162:165], v[102:105], v[34:49]
	v_max3_f32 v83, v83, v140, v141
	v_max3_f32 v82, v82, v139, v122
	v_max3_f32 v83, v83, v124, v125
	v_max3_f32 v82, v82, v123, v142
	v_max3_f32 v83, v83, v144, v145
	v_max3_f32 v82, v82, v143, v126
	v_max3_f32 v83, v83, v128, v129
	v_max3_f32 v82, v82, v127, v83
	v_mov_b32_e32 v83, v82
	v_add_u32_e32 v94, s43, v241
	v_add_u32_e32 v102, s40, v228
	v_permlane32_swap_b32_e32 v82, v83
	v_max_f32_e32 v82, v82, v83
	v_cmp_lt_f32_e32 vcc, s15, v82
	s_cbranch_vccnz .LBB0_1087

.LBB0_1094:
	s_setprio 0
	s_add_i32 s0, s8, 1
	s_cmp_lt_i32 s0, s46
	s_cbranch_scc1 .LBB0_1102
	s_lshl_b32 s42, s43, 1
	v_lshlrev_b32_e32 v114, 2, v220
	s_cbranch_execz .LBB0_1103
	v_mov_b32_e32 v236, v114
